# final_norm: gain vector loaded once, each row's 8 X loads issued together with counted vmcnt (one round trip per row instead of eight)
# speedup vs baseline: 1.0100x; 1.0097x over previous
; DI int opaque_tid() { int t = threadIdx.x; asm volatile("" : "+v"(t)); return t; }
; DI float ss_get(const ssacc_t* p) { const ssacc_t v = *p; return (float)(unsigned)(v >> 32) + (float)(unsigned)(v & 0xffffffffull) * 2.3283064365386963e-10f; }
; DI void final_norm(PP p) {
;     const int tid = opaque_tid(), lane = tid & 63, wid = __builtin_amdgcn_readfirstlane(tid >> 6);
;     const float* X = (const float*)(p->ws + WS_X); const ssacc_t* ss = (const ssacc_t*)(p->ws + WS_SS) + (size_t)(SS_X + 4) * M_; const float* g = p->in[25];
;     for (int m = blockIdx.x * 8 + wid; m < M_; m += gridDim.x * 8) {
;         const float rs = rsqrtf(ss_get(ss + m) * (1.f / 2048.f) + EPS_);
; #pragma unroll
;         for (int j = 0; j < 8; ++j) { const int c = j * 256 + lane * 4; const f32x4 v = *(const f32x4*)(X + (size_t)m * 2048 + c), gg = *(const f32x4*)(g + c); *(f32x4*)(p->out + (size_t)m * 2048 + c) = v * rs * gg; }
;     }
; }
.LBB0_1638:
	v_readlane_b32 s8, v253, 3
	v_readlane_b32 s9, v253, 4
	v_readlane_b32 s1, v253, 2
	v_readfirstlane_b32 s0, v188
	s_ashr_i32 s0, s0, 6
	s_add_i32 s0, s0, s1
	s_cmpk_gt_i32 s0, 0x1fff
	s_cbranch_scc1 .LBB0_1641
	s_load_dwordx2 s[2:3], s[8:9], 0xd8
	s_load_dwordx4 s[4:7], s[8:9], 0xc8
	v_lshlrev_b32_e32 v0, 2, v188
	v_and_b32_e32 v14, 0xfc, v0
	v_mov_b32_e32 v1, 0
	v_lshlrev_b32_e32 v0, 2, v14
	v_or_b32_e32 v16, 0x400, v14
	s_waitcnt lgkmcnt(0)
	s_add_u32 s8, s2, 0x16e00000
	v_lshl_add_u64 v[2:3], s[4:5], 0, v[0:1]
	v_lshlrev_b32_e32 v0, 2, v16
	v_or_b32_e32 v18, 0x500, v14
	s_addc_u32 s9, s3, 0
	v_lshl_add_u64 v[4:5], s[4:5], 0, v[0:1]
	v_lshlrev_b32_e32 v0, 2, v18
	v_or_b32_e32 v20, 0x600, v14
	s_add_u32 s10, s2, 0x29540000
	v_lshl_add_u64 v[6:7], s[4:5], 0, v[0:1]
	v_lshlrev_b32_e32 v0, 2, v20
	v_or_b32_e32 v22, 0x700, v14
	s_addc_u32 s11, s3, 0
	v_lshl_add_u64 v[8:9], s[4:5], 0, v[0:1]
	v_lshlrev_b32_e32 v0, 2, v22
	s_min_u32 s12, s88, 32
	v_lshl_add_u64 v[10:11], s[4:5], 0, v[0:1]
	s_sub_i32 s13, 32, s12
	v_mov_b32_e32 v12, 0x358637bd
	s_mov_b32 s14, 0x800000
	v_lshlrev_b32_e32 v13, 2, v14
	v_lshlrev_b32_e32 v14, 2, v16
	v_lshlrev_b32_e32 v15, 2, v18
	v_lshlrev_b32_e32 v16, 2, v20
	v_lshlrev_b32_e32 v17, 2, v22
	global_load_dwordx4 v[32:35], v[2:3], off
	global_load_dwordx4 v[36:39], v[2:3], off offset:1024
	global_load_dwordx4 v[40:43], v[2:3], off offset:2048
	global_load_dwordx4 v[44:47], v[2:3], off offset:3072
	global_load_dwordx4 v[48:51], v[4:5], off
	global_load_dwordx4 v[52:55], v[6:7], off
	global_load_dwordx4 v[56:59], v[8:9], off
	global_load_dwordx4 v[60:63], v[10:11], off
.LBB0_1640:
	s_ashr_i32 s1, s0, 31
	s_lshl_b64 s[2:3], s[0:1], 3
	s_add_u32 s2, s10, s2
	s_addc_u32 s3, s11, s3
	global_load_dwordx2 v[26:27], v1, s[2:3]
	s_lshl_b64 s[16:17], s[0:1], 13
	s_add_u32 s4, s8, s16
	s_addc_u32 s5, s9, s17
	global_load_dwordx4 v[64:67], v13, s[4:5]
	global_load_dwordx4 v[68:71], v13, s[4:5] offset:1024
	global_load_dwordx4 v[72:75], v13, s[4:5] offset:2048
	global_load_dwordx4 v[76:79], v13, s[4:5] offset:3072
	global_load_dwordx4 v[80:83], v14, s[4:5]
	global_load_dwordx4 v[84:87], v15, s[4:5]
	global_load_dwordx4 v[88:91], v16, s[4:5]
	global_load_dwordx4 v[92:95], v17, s[4:5]
	s_add_u32 s2, s6, s16
	s_addc_u32 s3, s7, s17
	s_add_i32 s0, s0, s94
	s_waitcnt vmcnt(8)
	v_mov_b32_e32 v0, v27
	v_cvt_f32_u32_e32 v28, v26
	v_lshlrev_b64 v[26:27], s12, v[0:1]
	v_min_u32_e32 v0, 1, v26
	v_or_b32_e32 v0, v27, v0
	v_cvt_f32_u32_e32 v0, v0
	v_ldexp_f32 v0, v0, s13
	v_fmac_f32_e32 v0, 0x2f800000, v28
	v_fmamk_f32 v0, v0, 0x3a000000, v12
	v_mul_f32_e32 v26, 0x4b800000, v0
	v_cmp_gt_f32_e32 vcc, s14, v0
	s_nop 1
	v_cndmask_b32_e32 v0, v0, v26, vcc
	v_rsq_f32_e32 v0, v0
	s_nop 0
	v_mul_f32_e32 v26, 0x45800000, v0
	v_cndmask_b32_e32 v0, v0, v26, vcc
	s_waitcnt vmcnt(7)
	v_pk_mul_f32 v[64:65], v[64:65], v[0:1] op_sel_hi:[1,0]
	v_pk_mul_f32 v[66:67], v[66:67], v[0:1] op_sel_hi:[1,0]
	v_pk_mul_f32 v[64:65], v[32:33], v[64:65]
	v_pk_mul_f32 v[66:67], v[34:35], v[66:67]
	global_store_dwordx4 v13, v[64:67], s[2:3]
	s_waitcnt vmcnt(7)
	v_pk_mul_f32 v[68:69], v[68:69], v[0:1] op_sel_hi:[1,0]
	v_pk_mul_f32 v[70:71], v[70:71], v[0:1] op_sel_hi:[1,0]
	v_pk_mul_f32 v[68:69], v[36:37], v[68:69]
	v_pk_mul_f32 v[70:71], v[38:39], v[70:71]
	global_store_dwordx4 v13, v[68:71], s[2:3] offset:1024
	s_waitcnt vmcnt(7)
	v_pk_mul_f32 v[72:73], v[72:73], v[0:1] op_sel_hi:[1,0]
	v_pk_mul_f32 v[74:75], v[74:75], v[0:1] op_sel_hi:[1,0]
	v_pk_mul_f32 v[72:73], v[40:41], v[72:73]
	v_pk_mul_f32 v[74:75], v[42:43], v[74:75]
	global_store_dwordx4 v13, v[72:75], s[2:3] offset:2048
	s_waitcnt vmcnt(7)
	v_pk_mul_f32 v[76:77], v[76:77], v[0:1] op_sel_hi:[1,0]
	v_pk_mul_f32 v[78:79], v[78:79], v[0:1] op_sel_hi:[1,0]
	v_pk_mul_f32 v[76:77], v[44:45], v[76:77]
	v_pk_mul_f32 v[78:79], v[46:47], v[78:79]
	global_store_dwordx4 v13, v[76:79], s[2:3] offset:3072
	s_waitcnt vmcnt(7)
	v_pk_mul_f32 v[80:81], v[80:81], v[0:1] op_sel_hi:[1,0]
	v_pk_mul_f32 v[82:83], v[82:83], v[0:1] op_sel_hi:[1,0]
	v_pk_mul_f32 v[80:81], v[48:49], v[80:81]
	v_pk_mul_f32 v[82:83], v[50:51], v[82:83]
	global_store_dwordx4 v14, v[80:83], s[2:3]
	s_waitcnt vmcnt(7)
	v_pk_mul_f32 v[84:85], v[84:85], v[0:1] op_sel_hi:[1,0]
	v_pk_mul_f32 v[86:87], v[86:87], v[0:1] op_sel_hi:[1,0]
	v_pk_mul_f32 v[84:85], v[52:53], v[84:85]
	v_pk_mul_f32 v[86:87], v[54:55], v[86:87]
	global_store_dwordx4 v15, v[84:87], s[2:3]
	s_waitcnt vmcnt(7)
	v_pk_mul_f32 v[88:89], v[88:89], v[0:1] op_sel_hi:[1,0]
	v_pk_mul_f32 v[90:91], v[90:91], v[0:1] op_sel_hi:[1,0]
	v_pk_mul_f32 v[88:89], v[56:57], v[88:89]
	v_pk_mul_f32 v[90:91], v[58:59], v[90:91]
	global_store_dwordx4 v16, v[88:91], s[2:3]
	s_waitcnt vmcnt(7)
	v_pk_mul_f32 v[92:93], v[92:93], v[0:1] op_sel_hi:[1,0]
	v_pk_mul_f32 v[94:95], v[94:95], v[0:1] op_sel_hi:[1,0]
	v_pk_mul_f32 v[92:93], v[60:61], v[92:93]
	v_pk_mul_f32 v[94:95], v[62:63], v[94:95]
	global_store_dwordx4 v17, v[92:95], s[2:3]
	s_cmpk_lt_i32 s0, 0x2000
	s_cbranch_scc1 .LBB0_1640
